# F1G epilogue: 8 serialized rss loads hoisted before main loop
# speedup vs baseline: 1.0010x; 1.0010x over previous
.LBB0_965:
	s_ashr_i32 s17, s16, 31
	s_lshl_b64 s[22:23], s[16:17], 20
	s_add_u32 s22, s2, s22
	s_addc_u32 s23, s3, s23
	s_and_b64 s[28:29], s[12:13], exec
	s_cselect_b32 s17, s23, s5
	s_cselect_b32 s25, s22, s4
	s_cmp_eq_u32 s50, 0
	s_cselect_b32 s34, s21, s33
	s_cselect_b32 s35, s20, s27
	s_ashr_i32 s15, s14, 31
	s_lshl_b64 s[28:29], s[14:15], 20
	s_add_u32 s28, s35, s28
	s_addc_u32 s29, s34, s29
	s_and_b64 s[34:35], s[12:13], exec
	s_cselect_b32 s15, s29, s31
	s_cselect_b32 s36, s28, s30
	s_add_u32 s4, s4, 0x80080
	s_addc_u32 s5, s5, 0
	s_add_u32 s37, s30, 0x100
	v_mov_b32_e32 v0, 0
	s_addc_u32 s51, s31, 0
	s_mov_b32 s52, -2
	v_mov_b32_e32 v1, v0
	v_mov_b32_e32 v2, v0
	v_mov_b32_e32 v3, v0
	v_mov_b32_e32 v4, v0
	v_mov_b32_e32 v5, v0
	v_mov_b32_e32 v6, v0
	v_mov_b32_e32 v7, v0
	v_mov_b32_e32 v16, v0
	v_mov_b32_e32 v17, v0
	v_mov_b32_e32 v18, v0
	v_mov_b32_e32 v19, v0
	v_mov_b32_e32 v20, v0
	v_mov_b32_e32 v21, v0
	v_mov_b32_e32 v22, v0
	v_mov_b32_e32 v23, v0
	v_mov_b32_e32 v32, v0
	v_mov_b32_e32 v33, v0
	v_mov_b32_e32 v34, v0
	v_mov_b32_e32 v35, v0
	v_mov_b32_e32 v36, v0
	v_mov_b32_e32 v37, v0
	v_mov_b32_e32 v38, v0
	v_mov_b32_e32 v39, v0
	v_mov_b32_e32 v48, v0
	v_mov_b32_e32 v49, v0
	v_mov_b32_e32 v50, v0
	v_mov_b32_e32 v51, v0
	v_mov_b32_e32 v52, v0
	v_mov_b32_e32 v53, v0
	v_mov_b32_e32 v54, v0
	v_mov_b32_e32 v55, v0
	v_mov_b32_e32 v8, v0
	v_mov_b32_e32 v9, v0
	v_mov_b32_e32 v10, v0
	v_mov_b32_e32 v11, v0
	v_mov_b32_e32 v12, v0
	v_mov_b32_e32 v13, v0
	v_mov_b32_e32 v14, v0
	v_mov_b32_e32 v15, v0
	v_mov_b32_e32 v24, v0
	v_mov_b32_e32 v25, v0
	v_mov_b32_e32 v26, v0
	v_mov_b32_e32 v27, v0
	v_mov_b32_e32 v28, v0
	v_mov_b32_e32 v29, v0
	v_mov_b32_e32 v30, v0
	v_mov_b32_e32 v31, v0
	v_mov_b32_e32 v40, v0
	v_mov_b32_e32 v41, v0
	v_mov_b32_e32 v42, v0
	v_mov_b32_e32 v43, v0
	v_mov_b32_e32 v44, v0
	v_mov_b32_e32 v45, v0
	v_mov_b32_e32 v46, v0
	v_mov_b32_e32 v47, v0
	v_mov_b32_e32 v56, v0
	v_mov_b32_e32 v57, v0
	v_mov_b32_e32 v58, v0
	v_mov_b32_e32 v59, v0
	v_mov_b32_e32 v60, v0
	v_mov_b32_e32 v61, v0
	v_mov_b32_e32 v62, v0
	v_mov_b32_e32 v63, v0
	v_mov_b32_e32 v64, v0
	v_mov_b32_e32 v65, v0
	v_mov_b32_e32 v66, v0
	v_mov_b32_e32 v67, v0
	v_mov_b32_e32 v68, v0
	v_mov_b32_e32 v69, v0
	v_mov_b32_e32 v70, v0
	v_mov_b32_e32 v71, v0
	v_mov_b32_e32 v80, v0
	v_mov_b32_e32 v81, v0
	v_mov_b32_e32 v82, v0
	v_mov_b32_e32 v83, v0
	v_mov_b32_e32 v84, v0
	v_mov_b32_e32 v85, v0
	v_mov_b32_e32 v86, v0
	v_mov_b32_e32 v87, v0
	v_mov_b32_e32 v96, v0
	v_mov_b32_e32 v97, v0
	v_mov_b32_e32 v98, v0
	v_mov_b32_e32 v99, v0
	v_mov_b32_e32 v100, v0
	v_mov_b32_e32 v101, v0
	v_mov_b32_e32 v102, v0
	v_mov_b32_e32 v103, v0
	v_mov_b32_e32 v112, v0
	v_mov_b32_e32 v113, v0
	v_mov_b32_e32 v114, v0
	v_mov_b32_e32 v115, v0
	v_mov_b32_e32 v116, v0
	v_mov_b32_e32 v117, v0
	v_mov_b32_e32 v118, v0
	v_mov_b32_e32 v119, v0
	v_mov_b32_e32 v72, v0
	v_mov_b32_e32 v73, v0
	v_mov_b32_e32 v74, v0
	v_mov_b32_e32 v75, v0
	v_mov_b32_e32 v76, v0
	v_mov_b32_e32 v77, v0
	v_mov_b32_e32 v78, v0
	v_mov_b32_e32 v79, v0
	v_mov_b32_e32 v88, v0
	v_mov_b32_e32 v89, v0
	v_mov_b32_e32 v90, v0
	v_mov_b32_e32 v91, v0
	v_mov_b32_e32 v92, v0
	v_mov_b32_e32 v93, v0
	v_mov_b32_e32 v94, v0
	v_mov_b32_e32 v95, v0
	v_mov_b32_e32 v104, v0
	v_mov_b32_e32 v105, v0
	v_mov_b32_e32 v106, v0
	v_mov_b32_e32 v107, v0
	v_mov_b32_e32 v108, v0
	v_mov_b32_e32 v109, v0
	v_mov_b32_e32 v110, v0
	v_mov_b32_e32 v111, v0
	v_mov_b32_e32 v120, v0
	v_mov_b32_e32 v121, v0
	v_mov_b32_e32 v122, v0
	v_mov_b32_e32 v123, v0
	v_mov_b32_e32 v124, v0
	v_mov_b32_e32 v125, v0
	v_mov_b32_e32 v126, v0
	v_mov_b32_e32 v127, v0
	s_cmp_lg_u32 s11, 0
	s_cbranch_scc1 .Lf1g_rss_skip
	s_lshl_b32 s60, s24, 10
	s_add_u32 s60, s45, s60
	s_addc_u32 s61, s46, 0
	v_lshl_add_u64 v[240:241], v[136:137], 2, s[60:61]
	global_load_dword v232, v[240:241], off
	global_load_dword v233, v[240:241], off offset:64
	global_load_dword v234, v[240:241], off offset:128
	global_load_dword v235, v[240:241], off offset:192
	global_load_dword v236, v[240:241], off offset:512
	global_load_dword v237, v[240:241], off offset:576
	global_load_dword v238, v[240:241], off offset:640
	global_load_dword v239, v[240:241], off offset:704
.Lf1g_rss_skip:
.LBB0_966:
	s_add_u32 s30, s4, 0xfff80080
	s_addc_u32 s31, s5, -1
	s_add_i32 s53, 0, 0x10000
	s_cmp_eq_u32 s52, 28
	s_cselect_b32 s35, s17, s31
	s_cselect_b32 s34, s25, s30
	v_add_u32_e32 v142, s53, v143
	s_cselect_b32 s31, s15, s51
	s_cselect_b32 s30, s36, s37
	s_add_i32 s56, 0, 0x14000
	ds_read_b128 v[148:151], v142
	ds_read_b128 v[152:155], v142 offset:1024
	ds_read_b128 v[156:159], v142 offset:2048
	ds_read_b128 v[160:163], v142 offset:3072
	v_add_u32_e32 v142, s56, v143
	ds_read_b128 v[164:167], v142
	ds_read_b128 v[168:171], v142 offset:1024
	ds_read_b128 v[172:175], v142 offset:2048
	ds_read_b128 v[178:181], v142 offset:3072
	v_lshl_add_u64 v[144:145], s[4:5], 0, v[138:139]
	s_add_i32 m0, s19, 0xc000
	ds_read_b128 v[182:185], v147
	ds_read_b128 v[186:189], v147 offset:1024
	ds_read_b128 v[190:193], v147 offset:2048
	ds_read_b128 v[194:197], v147 offset:3072
	ds_read_b128 v[198:201], v147 offset:4096
	ds_read_b128 v[202:205], v147 offset:5120
	ds_read_b128 v[206:209], v147 offset:6144
	ds_read_b128 v[220:223], v147 offset:7168
	global_load_lds_dwordx4 v[144:145], off
	v_lshl_add_u64 v[144:145], s[4:5], 0, v[140:141]
	s_add_i32 m0, s19, 0xe000
	s_nop 0
	global_load_lds_dwordx4 v[144:145], off
	s_waitcnt vmcnt(8)
	s_waitcnt lgkmcnt(0)
	s_barrier
	s_setprio 1
	s_waitcnt lgkmcnt(0)
	v_mfma_f32_16x16x32_bf16 v[124:127], v[148:151], v[182:185], v[124:127]
	v_mfma_f32_16x16x32_bf16 v[120:123], v[156:159], v[182:185], v[120:123]
	v_mfma_f32_16x16x32_bf16 v[108:111], v[148:151], v[190:193], v[108:111]
	v_mfma_f32_16x16x32_bf16 v[104:107], v[156:159], v[190:193], v[104:107]
	v_mfma_f32_16x16x32_bf16 v[92:95], v[148:151], v[198:201], v[92:95]
	v_mfma_f32_16x16x32_bf16 v[88:91], v[156:159], v[198:201], v[88:91]
	v_mfma_f32_16x16x32_bf16 v[76:79], v[148:151], v[206:209], v[76:79]
	v_mfma_f32_16x16x32_bf16 v[72:75], v[156:159], v[206:209], v[72:75]
	v_mfma_f32_16x16x32_bf16 v[124:127], v[152:155], v[186:189], v[124:127]
	v_mfma_f32_16x16x32_bf16 v[120:123], v[160:163], v[186:189], v[120:123]
	v_mfma_f32_16x16x32_bf16 v[108:111], v[152:155], v[194:197], v[108:111]
	v_mfma_f32_16x16x32_bf16 v[104:107], v[160:163], v[194:197], v[104:107]
	v_mfma_f32_16x16x32_bf16 v[92:95], v[152:155], v[202:205], v[92:95]
	v_mfma_f32_16x16x32_bf16 v[88:91], v[160:163], v[202:205], v[88:91]
	v_mfma_f32_16x16x32_bf16 v[76:79], v[152:155], v[220:223], v[76:79]
	v_mfma_f32_16x16x32_bf16 v[72:75], v[160:163], v[220:223], v[72:75]
	s_setprio 0
	s_setprio 1
	v_mfma_f32_16x16x32_bf16 v[116:119], v[164:167], v[182:185], v[116:119]
	v_mfma_f32_16x16x32_bf16 v[112:115], v[172:175], v[182:185], v[112:115]
	v_mfma_f32_16x16x32_bf16 v[100:103], v[164:167], v[190:193], v[100:103]
	v_mfma_f32_16x16x32_bf16 v[96:99], v[172:175], v[190:193], v[96:99]
	v_mfma_f32_16x16x32_bf16 v[84:87], v[164:167], v[198:201], v[84:87]
	v_mfma_f32_16x16x32_bf16 v[80:83], v[172:175], v[198:201], v[80:83]
	v_mfma_f32_16x16x32_bf16 v[68:71], v[164:167], v[206:209], v[68:71]
	v_mfma_f32_16x16x32_bf16 v[64:67], v[172:175], v[206:209], v[64:67]
	v_mfma_f32_16x16x32_bf16 v[116:119], v[168:171], v[186:189], v[116:119]
	v_mfma_f32_16x16x32_bf16 v[112:115], v[178:181], v[186:189], v[112:115]
	v_mfma_f32_16x16x32_bf16 v[100:103], v[168:171], v[194:197], v[100:103]
	v_mfma_f32_16x16x32_bf16 v[96:99], v[178:181], v[194:197], v[96:99]
	v_mfma_f32_16x16x32_bf16 v[84:87], v[168:171], v[202:205], v[84:87]
	v_mfma_f32_16x16x32_bf16 v[80:83], v[178:181], v[202:205], v[80:83]
	v_mfma_f32_16x16x32_bf16 v[68:71], v[168:171], v[220:223], v[68:71]
	v_mfma_f32_16x16x32_bf16 v[64:67], v[178:181], v[220:223], v[64:67]
	s_setprio 0
	s_barrier
	s_add_i32 s53, s53, s26
	v_lshl_add_u64 v[144:145], s[30:31], 0, v[130:131]
	s_mov_b32 m0, s53
	ds_read_b128 v[182:185], v147 offset:16384
	ds_read_b128 v[186:189], v147 offset:17408
	ds_read_b128 v[190:193], v147 offset:18432
	ds_read_b128 v[194:197], v147 offset:19456
	ds_read_b128 v[198:201], v147 offset:20480
	ds_read_b128 v[202:205], v147 offset:21504
	ds_read_b128 v[206:209], v147 offset:22528
	ds_read_b128 v[220:223], v147 offset:23552
	global_load_lds_dwordx4 v[144:145], off
	s_add_i32 m0, s53, 0x2000
	s_add_u32 s54, s30, 0x80000
	v_lshl_add_u64 v[224:225], s[30:31], 0, v[134:135]
	s_addc_u32 s55, s31, 0
	s_add_i32 s53, s56, s26
	global_load_lds_dwordx4 v[224:225], off
	v_lshl_add_u64 v[226:227], s[54:55], 0, v[130:131]
	s_mov_b32 m0, s53
	v_lshl_add_u64 v[228:229], s[34:35], 0, v[132:133]
	global_load_lds_dwordx4 v[226:227], off
	v_lshl_add_u64 v[226:227], s[54:55], 0, v[134:135]
	s_add_i32 m0, s53, 0x2000
	s_nop 0
	global_load_lds_dwordx4 v[226:227], off
	v_lshl_add_u64 v[226:227], s[34:35], 0, v[128:129]
	s_mov_b32 m0, s19
	s_nop 0
	global_load_lds_dwordx4 v[226:227], off
	s_mov_b32 m0, s38
	s_nop 0
	global_load_lds_dwordx4 v[228:229], off
	s_waitcnt vmcnt(8)
	s_waitcnt lgkmcnt(0)
	s_barrier
	s_setprio 1
	s_waitcnt lgkmcnt(0)
	v_mfma_f32_16x16x32_bf16 v[60:63], v[148:151], v[182:185], v[60:63]
	v_mfma_f32_16x16x32_bf16 v[56:59], v[156:159], v[182:185], v[56:59]
	v_mfma_f32_16x16x32_bf16 v[44:47], v[148:151], v[190:193], v[44:47]
	v_mfma_f32_16x16x32_bf16 v[40:43], v[156:159], v[190:193], v[40:43]
	v_mfma_f32_16x16x32_bf16 v[28:31], v[148:151], v[198:201], v[28:31]
	v_mfma_f32_16x16x32_bf16 v[24:27], v[156:159], v[198:201], v[24:27]
	v_mfma_f32_16x16x32_bf16 v[12:15], v[148:151], v[206:209], v[12:15]
	v_mfma_f32_16x16x32_bf16 v[8:11], v[156:159], v[206:209], v[8:11]
	v_mfma_f32_16x16x32_bf16 v[60:63], v[152:155], v[186:189], v[60:63]
	v_mfma_f32_16x16x32_bf16 v[56:59], v[160:163], v[186:189], v[56:59]
	v_mfma_f32_16x16x32_bf16 v[44:47], v[152:155], v[194:197], v[44:47]
	v_mfma_f32_16x16x32_bf16 v[40:43], v[160:163], v[194:197], v[40:43]
	v_mfma_f32_16x16x32_bf16 v[28:31], v[152:155], v[202:205], v[28:31]
	v_mfma_f32_16x16x32_bf16 v[24:27], v[160:163], v[202:205], v[24:27]
	v_mfma_f32_16x16x32_bf16 v[12:15], v[152:155], v[220:223], v[12:15]
	v_mfma_f32_16x16x32_bf16 v[8:11], v[160:163], v[220:223], v[8:11]
	s_setprio 0
	s_setprio 1
	v_mfma_f32_16x16x32_bf16 v[52:55], v[164:167], v[182:185], v[52:55]
	v_mfma_f32_16x16x32_bf16 v[48:51], v[172:175], v[182:185], v[48:51]
	v_mfma_f32_16x16x32_bf16 v[36:39], v[164:167], v[190:193], v[36:39]
	v_mfma_f32_16x16x32_bf16 v[32:35], v[172:175], v[190:193], v[32:35]
	v_mfma_f32_16x16x32_bf16 v[20:23], v[164:167], v[198:201], v[20:23]
	v_mfma_f32_16x16x32_bf16 v[16:19], v[172:175], v[198:201], v[16:19]
	v_mfma_f32_16x16x32_bf16 v[4:7], v[164:167], v[206:209], v[4:7]
	v_mfma_f32_16x16x32_bf16 v[0:3], v[172:175], v[206:209], v[0:3]
	v_mfma_f32_16x16x32_bf16 v[52:55], v[168:171], v[186:189], v[52:55]
	v_mfma_f32_16x16x32_bf16 v[48:51], v[178:181], v[186:189], v[48:51]
	v_mfma_f32_16x16x32_bf16 v[36:39], v[168:171], v[194:197], v[36:39]
	v_mfma_f32_16x16x32_bf16 v[32:35], v[178:181], v[194:197], v[32:35]
	v_mfma_f32_16x16x32_bf16 v[20:23], v[168:171], v[202:205], v[20:23]
	v_mfma_f32_16x16x32_bf16 v[16:19], v[178:181], v[202:205], v[16:19]
	v_mfma_f32_16x16x32_bf16 v[4:7], v[168:171], v[220:223], v[4:7]
	v_mfma_f32_16x16x32_bf16 v[0:3], v[178:181], v[220:223], v[0:3]
	s_setprio 0
	s_barrier
	s_add_i32 s53, 0, 0x18000
	v_add_u32_e32 v142, s53, v143
	s_add_i32 s54, 0, 0x1c000
	ds_read_b128 v[148:151], v142
	ds_read_b128 v[152:155], v142 offset:1024
	ds_read_b128 v[156:159], v142 offset:2048
	ds_read_b128 v[160:163], v142 offset:3072
	v_add_u32_e32 v142, s54, v143
	ds_read_b128 v[164:167], v142
	ds_read_b128 v[168:171], v142 offset:1024
	ds_read_b128 v[172:175], v142 offset:2048
	ds_read_b128 v[178:181], v142 offset:3072
	s_add_u32 s34, s34, 0x80000
	s_addc_u32 s35, s35, 0
	s_mov_b32 m0, s39
	v_lshl_add_u64 v[230:231], s[34:35], 0, v[128:129]
	ds_read_b128 v[182:185], v147 offset:32768
	ds_read_b128 v[186:189], v147 offset:33792
	ds_read_b128 v[190:193], v147 offset:34816
	ds_read_b128 v[194:197], v147 offset:35840
	ds_read_b128 v[198:201], v147 offset:36864
	ds_read_b128 v[202:205], v147 offset:37888
	ds_read_b128 v[206:209], v147 offset:38912
	ds_read_b128 v[220:223], v147 offset:39936
	global_load_lds_dwordx4 v[230:231], off
	v_lshl_add_u64 v[230:231], s[34:35], 0, v[132:133]
	s_mov_b32 m0, s40
	s_nop 0
	global_load_lds_dwordx4 v[230:231], off
	s_waitcnt vmcnt(8)
	s_waitcnt lgkmcnt(0)
	s_barrier
	s_setprio 1
	s_waitcnt lgkmcnt(0)
	v_mfma_f32_16x16x32_bf16 v[124:127], v[148:151], v[182:185], v[124:127]
	v_mfma_f32_16x16x32_bf16 v[120:123], v[156:159], v[182:185], v[120:123]
	v_mfma_f32_16x16x32_bf16 v[108:111], v[148:151], v[190:193], v[108:111]
	v_mfma_f32_16x16x32_bf16 v[104:107], v[156:159], v[190:193], v[104:107]
	v_mfma_f32_16x16x32_bf16 v[92:95], v[148:151], v[198:201], v[92:95]
	v_mfma_f32_16x16x32_bf16 v[88:91], v[156:159], v[198:201], v[88:91]
	v_mfma_f32_16x16x32_bf16 v[76:79], v[148:151], v[206:209], v[76:79]
	v_mfma_f32_16x16x32_bf16 v[72:75], v[156:159], v[206:209], v[72:75]
	v_mfma_f32_16x16x32_bf16 v[124:127], v[152:155], v[186:189], v[124:127]
	v_mfma_f32_16x16x32_bf16 v[120:123], v[160:163], v[186:189], v[120:123]
	v_mfma_f32_16x16x32_bf16 v[108:111], v[152:155], v[194:197], v[108:111]
	v_mfma_f32_16x16x32_bf16 v[104:107], v[160:163], v[194:197], v[104:107]
	v_mfma_f32_16x16x32_bf16 v[92:95], v[152:155], v[202:205], v[92:95]
	v_mfma_f32_16x16x32_bf16 v[88:91], v[160:163], v[202:205], v[88:91]
	v_mfma_f32_16x16x32_bf16 v[76:79], v[152:155], v[220:223], v[76:79]
	v_mfma_f32_16x16x32_bf16 v[72:75], v[160:163], v[220:223], v[72:75]
	s_setprio 0
	s_setprio 1
	v_mfma_f32_16x16x32_bf16 v[116:119], v[164:167], v[182:185], v[116:119]
	v_mfma_f32_16x16x32_bf16 v[112:115], v[172:175], v[182:185], v[112:115]
	v_mfma_f32_16x16x32_bf16 v[100:103], v[164:167], v[190:193], v[100:103]
	v_mfma_f32_16x16x32_bf16 v[96:99], v[172:175], v[190:193], v[96:99]
	v_mfma_f32_16x16x32_bf16 v[84:87], v[164:167], v[198:201], v[84:87]
	v_mfma_f32_16x16x32_bf16 v[80:83], v[172:175], v[198:201], v[80:83]
	v_mfma_f32_16x16x32_bf16 v[68:71], v[164:167], v[206:209], v[68:71]
	v_mfma_f32_16x16x32_bf16 v[64:67], v[172:175], v[206:209], v[64:67]
	v_mfma_f32_16x16x32_bf16 v[116:119], v[168:171], v[186:189], v[116:119]
	v_mfma_f32_16x16x32_bf16 v[112:115], v[178:181], v[186:189], v[112:115]
	v_mfma_f32_16x16x32_bf16 v[100:103], v[168:171], v[194:197], v[100:103]
	v_mfma_f32_16x16x32_bf16 v[96:99], v[178:181], v[194:197], v[96:99]
	v_mfma_f32_16x16x32_bf16 v[84:87], v[168:171], v[202:205], v[84:87]
	v_mfma_f32_16x16x32_bf16 v[80:83], v[178:181], v[202:205], v[80:83]
	v_mfma_f32_16x16x32_bf16 v[68:71], v[168:171], v[220:223], v[68:71]
	v_mfma_f32_16x16x32_bf16 v[64:67], v[178:181], v[220:223], v[64:67]
	s_setprio 0
	s_barrier
	s_add_i32 s34, s53, s26
	v_lshl_add_u64 v[144:145], v[144:145], 0, s[74:75]
	s_mov_b32 m0, s34
	ds_read_b128 v[182:185], v147 offset:49152
	ds_read_b128 v[186:189], v147 offset:50176
	ds_read_b128 v[190:193], v147 offset:51200
	ds_read_b128 v[194:197], v147 offset:52224
	ds_read_b128 v[198:201], v147 offset:53248
	ds_read_b128 v[202:205], v147 offset:54272
	ds_read_b128 v[206:209], v147 offset:55296
	ds_read_b128 v[220:223], v147 offset:56320
	global_load_lds_dwordx4 v[144:145], off
	s_add_i32 m0, s34, 0x2000
	s_add_u32 s30, s30, 0x80080
	v_lshl_add_u64 v[144:145], v[224:225], 0, s[74:75]
	s_addc_u32 s31, s31, 0
	s_add_i32 s34, s54, s26
	global_load_lds_dwordx4 v[144:145], off
	v_lshl_add_u64 v[144:145], s[30:31], 0, v[130:131]
	s_mov_b32 m0, s34
	s_nop 0
	global_load_lds_dwordx4 v[144:145], off
	v_lshl_add_u64 v[144:145], s[30:31], 0, v[134:135]
	s_add_i32 m0, s34, 0x2000
	s_nop 0
	global_load_lds_dwordx4 v[144:145], off
	v_lshl_add_u64 v[144:145], v[226:227], 0, s[74:75]
	s_mov_b32 m0, s47
	s_nop 0
	global_load_lds_dwordx4 v[144:145], off
	v_lshl_add_u64 v[144:145], v[228:229], 0, s[74:75]
	s_mov_b32 m0, s48
	s_nop 0
	global_load_lds_dwordx4 v[144:145], off
	s_waitcnt vmcnt(8)
	s_waitcnt lgkmcnt(0)
	s_barrier
	s_setprio 1
	s_waitcnt lgkmcnt(0)
	v_mfma_f32_16x16x32_bf16 v[60:63], v[148:151], v[182:185], v[60:63]
	v_mfma_f32_16x16x32_bf16 v[56:59], v[156:159], v[182:185], v[56:59]
	v_mfma_f32_16x16x32_bf16 v[44:47], v[148:151], v[190:193], v[44:47]
	v_mfma_f32_16x16x32_bf16 v[40:43], v[156:159], v[190:193], v[40:43]
	v_mfma_f32_16x16x32_bf16 v[28:31], v[148:151], v[198:201], v[28:31]
	v_mfma_f32_16x16x32_bf16 v[24:27], v[156:159], v[198:201], v[24:27]
	v_mfma_f32_16x16x32_bf16 v[12:15], v[148:151], v[206:209], v[12:15]
	v_mfma_f32_16x16x32_bf16 v[8:11], v[156:159], v[206:209], v[8:11]
	v_mfma_f32_16x16x32_bf16 v[60:63], v[152:155], v[186:189], v[60:63]
	v_mfma_f32_16x16x32_bf16 v[56:59], v[160:163], v[186:189], v[56:59]
	v_mfma_f32_16x16x32_bf16 v[44:47], v[152:155], v[194:197], v[44:47]
	v_mfma_f32_16x16x32_bf16 v[40:43], v[160:163], v[194:197], v[40:43]
	v_mfma_f32_16x16x32_bf16 v[28:31], v[152:155], v[202:205], v[28:31]
	v_mfma_f32_16x16x32_bf16 v[24:27], v[160:163], v[202:205], v[24:27]
	v_mfma_f32_16x16x32_bf16 v[12:15], v[152:155], v[220:223], v[12:15]
	v_mfma_f32_16x16x32_bf16 v[8:11], v[160:163], v[220:223], v[8:11]
	s_setprio 0
	s_setprio 1
	v_mfma_f32_16x16x32_bf16 v[52:55], v[164:167], v[182:185], v[52:55]
	v_mfma_f32_16x16x32_bf16 v[48:51], v[172:175], v[182:185], v[48:51]
	v_mfma_f32_16x16x32_bf16 v[36:39], v[164:167], v[190:193], v[36:39]
	v_mfma_f32_16x16x32_bf16 v[32:35], v[172:175], v[190:193], v[32:35]
	v_mfma_f32_16x16x32_bf16 v[20:23], v[164:167], v[198:201], v[20:23]
	v_mfma_f32_16x16x32_bf16 v[16:19], v[172:175], v[198:201], v[16:19]
	v_mfma_f32_16x16x32_bf16 v[4:7], v[164:167], v[206:209], v[4:7]
	v_mfma_f32_16x16x32_bf16 v[0:3], v[172:175], v[206:209], v[0:3]
	v_mfma_f32_16x16x32_bf16 v[52:55], v[168:171], v[186:189], v[52:55]
	v_mfma_f32_16x16x32_bf16 v[48:51], v[178:181], v[186:189], v[48:51]
	v_mfma_f32_16x16x32_bf16 v[36:39], v[168:171], v[194:197], v[36:39]
	v_mfma_f32_16x16x32_bf16 v[32:35], v[178:181], v[194:197], v[32:35]
	v_mfma_f32_16x16x32_bf16 v[20:23], v[168:171], v[202:205], v[20:23]
	v_mfma_f32_16x16x32_bf16 v[16:19], v[178:181], v[202:205], v[16:19]
	v_mfma_f32_16x16x32_bf16 v[4:7], v[168:171], v[220:223], v[4:7]
	v_mfma_f32_16x16x32_bf16 v[0:3], v[178:181], v[220:223], v[0:3]
	s_setprio 0
	s_barrier
	s_add_i32 s52, s52, 2
	s_add_u32 s4, s4, 0x100
	s_addc_u32 s5, s5, 0
	s_add_u32 s37, s37, 0x100
	s_addc_u32 s51, s51, 0
	s_cmp_gt_u32 s52, 29
	s_cbranch_scc0 .LBB0_966
	s_and_b64 vcc, exec, s[8:9]
	s_cbranch_vccz .LBB0_969
	s_barrier

.LBB0_973:
	s_lshl_b32 s4, s24, 8
	s_ashr_i32 s5, s4, 31
	s_lshl_b64 s[4:5], s[4:5], 2
	s_add_u32 s24, s45, s4
	v_cndmask_b32_e64 v144, 0, 1, s[36:37]
	s_addc_u32 s25, s46, s5
	v_mov_b32_e32 v142, 1.0
	v_cmp_ne_u32_e64 s[4:5], 1, v144
	s_andn2_b64 vcc, exec, s[36:37]
	v_mov_b32_e32 v146, 1.0
	s_cbranch_vccnz .LBB0_975
	s_waitcnt vmcnt(8)
	v_cvt_f32_u32_e32 v144, v232
	v_fmamk_f32 v144, v144, 0x33000000, v213
	v_rsq_f32_e32 v146, v144
.LBB0_975:
	s_lshl_b32 s36, s18, 8
	s_ashr_i32 s37, s36, 31
	s_lshl_b64 s[36:37], s[36:37], 1
	s_add_u32 s34, s34, s36
	v_mad_i64_i32 v[144:145], s[52:53], s30, v136, 0
	s_addc_u32 s35, s35, s37
	v_lshl_add_u64 v[144:145], v[144:145], 1, s[34:35]
	s_mov_b32 s11, s73
	v_lshl_add_u64 v[144:145], v[144:145], 0, s[10:11]
	v_pk_mul_f32 v[126:127], v[126:127], v[146:147] op_sel_hi:[1,0]
	v_pk_mul_f32 v[124:125], v[124:125], v[146:147] op_sel_hi:[1,0]
	v_pk_mul_f32 v[148:149], v[122:123], v[146:147] op_sel_hi:[1,0]
	v_pk_mul_f32 v[122:123], v[120:121], v[146:147] op_sel_hi:[1,0]
	v_lshl_add_u64 v[144:145], v[144:145], 0, v[176:177]
	v_cvt_pk_bf16_f32 v120, v124, v125
	v_cvt_pk_bf16_f32 v121, v126, v127
	v_cvt_pk_bf16_f32 v122, v122, v123
	v_cvt_pk_bf16_f32 v123, v148, v149
	global_store_dwordx4 v[144:145], v[120:123], off
	v_pk_mul_f32 v[118:119], v[118:119], v[146:147] op_sel_hi:[1,0]
	v_pk_mul_f32 v[116:117], v[116:117], v[146:147] op_sel_hi:[1,0]
	v_pk_mul_f32 v[120:121], v[114:115], v[146:147] op_sel_hi:[1,0]
	v_pk_mul_f32 v[114:115], v[112:113], v[146:147] op_sel_hi:[1,0]
	v_cvt_pk_bf16_f32 v112, v116, v117
	v_cvt_pk_bf16_f32 v113, v118, v119
	v_cvt_pk_bf16_f32 v114, v114, v115
	v_cvt_pk_bf16_f32 v115, v120, v121
	s_and_b64 vcc, exec, s[4:5]
	global_store_dwordx4 v[144:145], v[112:115], off offset:256
	s_cbranch_vccnz .LBB0_977
	s_nop 0
	v_cvt_f32_u32_e32 v112, v233
	v_fmamk_f32 v112, v112, 0x33000000, v213
	v_rsq_f32_e32 v142, v112
.LBB0_977:
	s_lshl_b32 s72, s30, 5
	v_pk_mul_f32 v[110:111], v[110:111], v[142:143] op_sel_hi:[1,0]
	v_pk_mul_f32 v[108:109], v[108:109], v[142:143] op_sel_hi:[1,0]
	v_pk_mul_f32 v[114:115], v[106:107], v[142:143] op_sel_hi:[1,0]
	v_pk_mul_f32 v[106:107], v[104:105], v[142:143] op_sel_hi:[1,0]
	v_lshl_add_u64 v[112:113], v[144:145], 0, s[72:73]
	v_cvt_pk_bf16_f32 v104, v108, v109
	v_cvt_pk_bf16_f32 v105, v110, v111
	v_cvt_pk_bf16_f32 v106, v106, v107
	v_cvt_pk_bf16_f32 v107, v114, v115
	global_store_dwordx4 v[112:113], v[104:107], off
	v_pk_mul_f32 v[102:103], v[102:103], v[142:143] op_sel_hi:[1,0]
	v_pk_mul_f32 v[100:101], v[100:101], v[142:143] op_sel_hi:[1,0]
	v_pk_mul_f32 v[104:105], v[98:99], v[142:143] op_sel_hi:[1,0]
	v_pk_mul_f32 v[98:99], v[96:97], v[142:143] op_sel_hi:[1,0]
	v_cvt_pk_bf16_f32 v96, v100, v101
	v_cvt_pk_bf16_f32 v97, v102, v103
	v_cvt_pk_bf16_f32 v98, v98, v99
	v_cvt_pk_bf16_f32 v99, v104, v105
	global_store_dwordx4 v[112:113], v[96:99], off offset:256
	s_and_b64 vcc, exec, s[4:5]
	v_mov_b32_e32 v100, 1.0
	v_mov_b32_e32 v96, 1.0
	s_cbranch_vccnz .LBB0_979
	v_cvt_f32_u32_e32 v97, v234
	v_fmamk_f32 v97, v97, 0x33000000, v213
	v_rsq_f32_e32 v100, v97
.LBB0_979:
	s_nop 0
	v_pk_mul_f32 v[94:95], v[94:95], v[100:101] op_sel_hi:[1,0]
	v_pk_mul_f32 v[92:93], v[92:93], v[100:101] op_sel_hi:[1,0]
	v_pk_mul_f32 v[102:103], v[90:91], v[100:101] op_sel_hi:[1,0]
	v_pk_mul_f32 v[90:91], v[88:89], v[100:101] op_sel_hi:[1,0]
	v_lshl_add_u64 v[98:99], v[112:113], 0, s[72:73]
	v_cvt_pk_bf16_f32 v88, v92, v93
	v_cvt_pk_bf16_f32 v89, v94, v95
	v_cvt_pk_bf16_f32 v90, v90, v91
	v_cvt_pk_bf16_f32 v91, v102, v103
	global_store_dwordx4 v[98:99], v[88:91], off
	v_pk_mul_f32 v[86:87], v[86:87], v[100:101] op_sel_hi:[1,0]
	v_pk_mul_f32 v[84:85], v[84:85], v[100:101] op_sel_hi:[1,0]
	v_pk_mul_f32 v[88:89], v[82:83], v[100:101] op_sel_hi:[1,0]
	v_pk_mul_f32 v[82:83], v[80:81], v[100:101] op_sel_hi:[1,0]
	v_cvt_pk_bf16_f32 v80, v84, v85
	v_cvt_pk_bf16_f32 v81, v86, v87
	v_cvt_pk_bf16_f32 v82, v82, v83
	v_cvt_pk_bf16_f32 v83, v88, v89
	s_and_b64 vcc, exec, s[4:5]
	global_store_dwordx4 v[98:99], v[80:83], off offset:256
	s_cbranch_vccnz .LBB0_981
	s_nop 0
	v_cvt_f32_u32_e32 v80, v235
	v_fmamk_f32 v80, v80, 0x33000000, v213
	v_rsq_f32_e32 v96, v80
.LBB0_981:
	s_nop 0
	v_pk_mul_f32 v[78:79], v[78:79], v[96:97] op_sel_hi:[1,0]
	v_pk_mul_f32 v[76:77], v[76:77], v[96:97] op_sel_hi:[1,0]
	v_pk_mul_f32 v[82:83], v[74:75], v[96:97] op_sel_hi:[1,0]
	v_pk_mul_f32 v[74:75], v[72:73], v[96:97] op_sel_hi:[1,0]
	v_lshl_add_u64 v[80:81], v[98:99], 0, s[72:73]
	v_cvt_pk_bf16_f32 v72, v76, v77
	v_cvt_pk_bf16_f32 v73, v78, v79
	v_cvt_pk_bf16_f32 v74, v74, v75
	v_cvt_pk_bf16_f32 v75, v82, v83
	global_store_dwordx4 v[80:81], v[72:75], off
	v_pk_mul_f32 v[70:71], v[70:71], v[96:97] op_sel_hi:[1,0]
	v_pk_mul_f32 v[68:69], v[68:69], v[96:97] op_sel_hi:[1,0]
	v_pk_mul_f32 v[72:73], v[66:67], v[96:97] op_sel_hi:[1,0]
	v_pk_mul_f32 v[66:67], v[64:65], v[96:97] op_sel_hi:[1,0]
	v_cvt_pk_bf16_f32 v64, v68, v69
	v_cvt_pk_bf16_f32 v65, v70, v71
	v_cvt_pk_bf16_f32 v66, v66, v67
	v_cvt_pk_bf16_f32 v67, v72, v73
	global_store_dwordx4 v[80:81], v[64:67], off offset:256
	s_and_b64 vcc, exec, s[4:5]
	v_mov_b32_e32 v68, 1.0
	v_mov_b32_e32 v64, 1.0
	s_cbranch_vccnz .LBB0_983
	v_cvt_f32_u32_e32 v65, v236
	v_fmamk_f32 v65, v65, 0x33000000, v213
	v_rsq_f32_e32 v68, v65
.LBB0_983:
	s_mulk_i32 s30, 0xa0
	s_mov_b32 s31, s73
	v_pk_mul_f32 v[62:63], v[62:63], v[68:69] op_sel_hi:[1,0]
	v_pk_mul_f32 v[60:61], v[60:61], v[68:69] op_sel_hi:[1,0]
	v_pk_mul_f32 v[70:71], v[58:59], v[68:69] op_sel_hi:[1,0]
	v_pk_mul_f32 v[58:59], v[56:57], v[68:69] op_sel_hi:[1,0]
	v_lshl_add_u64 v[66:67], v[80:81], 0, s[30:31]
	v_cvt_pk_bf16_f32 v56, v60, v61
	v_cvt_pk_bf16_f32 v57, v62, v63
	v_cvt_pk_bf16_f32 v58, v58, v59
	v_cvt_pk_bf16_f32 v59, v70, v71
	global_store_dwordx4 v[66:67], v[56:59], off
	v_pk_mul_f32 v[54:55], v[54:55], v[68:69] op_sel_hi:[1,0]
	v_pk_mul_f32 v[52:53], v[52:53], v[68:69] op_sel_hi:[1,0]
	v_pk_mul_f32 v[56:57], v[50:51], v[68:69] op_sel_hi:[1,0]
	v_pk_mul_f32 v[50:51], v[48:49], v[68:69] op_sel_hi:[1,0]
	v_cvt_pk_bf16_f32 v48, v52, v53
	v_cvt_pk_bf16_f32 v49, v54, v55
	v_cvt_pk_bf16_f32 v50, v50, v51
	v_cvt_pk_bf16_f32 v51, v56, v57
	s_and_b64 vcc, exec, s[4:5]
	global_store_dwordx4 v[66:67], v[48:51], off offset:256
	s_cbranch_vccnz .LBB0_985
	s_nop 0
	v_cvt_f32_u32_e32 v48, v237
	v_fmamk_f32 v48, v48, 0x33000000, v213
	v_rsq_f32_e32 v64, v48
.LBB0_985:
	s_nop 0
	v_pk_mul_f32 v[46:47], v[46:47], v[64:65] op_sel_hi:[1,0]
	v_pk_mul_f32 v[44:45], v[44:45], v[64:65] op_sel_hi:[1,0]
	v_pk_mul_f32 v[50:51], v[42:43], v[64:65] op_sel_hi:[1,0]
	v_pk_mul_f32 v[42:43], v[40:41], v[64:65] op_sel_hi:[1,0]
	v_lshl_add_u64 v[48:49], v[66:67], 0, s[72:73]
	v_cvt_pk_bf16_f32 v40, v44, v45
	v_cvt_pk_bf16_f32 v41, v46, v47
	v_cvt_pk_bf16_f32 v42, v42, v43
	v_cvt_pk_bf16_f32 v43, v50, v51
	global_store_dwordx4 v[48:49], v[40:43], off
	v_pk_mul_f32 v[38:39], v[38:39], v[64:65] op_sel_hi:[1,0]
	v_pk_mul_f32 v[36:37], v[36:37], v[64:65] op_sel_hi:[1,0]
	v_pk_mul_f32 v[40:41], v[34:35], v[64:65] op_sel_hi:[1,0]
	v_pk_mul_f32 v[34:35], v[32:33], v[64:65] op_sel_hi:[1,0]
	v_cvt_pk_bf16_f32 v32, v36, v37
	v_cvt_pk_bf16_f32 v33, v38, v39
	v_cvt_pk_bf16_f32 v34, v34, v35
	v_cvt_pk_bf16_f32 v35, v40, v41
	global_store_dwordx4 v[48:49], v[32:35], off offset:256
	s_and_b64 vcc, exec, s[4:5]
	v_mov_b32_e32 v36, 1.0
	v_mov_b32_e32 v32, 1.0
	s_cbranch_vccnz .LBB0_987
	v_cvt_f32_u32_e32 v33, v238
	v_fmamk_f32 v33, v33, 0x33000000, v213
	v_rsq_f32_e32 v36, v33
.LBB0_987:
	s_nop 0
	v_pk_mul_f32 v[30:31], v[30:31], v[36:37] op_sel_hi:[1,0]
	v_pk_mul_f32 v[28:29], v[28:29], v[36:37] op_sel_hi:[1,0]
	v_pk_mul_f32 v[38:39], v[26:27], v[36:37] op_sel_hi:[1,0]
	v_pk_mul_f32 v[26:27], v[24:25], v[36:37] op_sel_hi:[1,0]
	v_lshl_add_u64 v[34:35], v[48:49], 0, s[72:73]
	v_cvt_pk_bf16_f32 v24, v28, v29
	v_cvt_pk_bf16_f32 v25, v30, v31
	v_cvt_pk_bf16_f32 v26, v26, v27
	v_cvt_pk_bf16_f32 v27, v38, v39
	global_store_dwordx4 v[34:35], v[24:27], off
	v_pk_mul_f32 v[22:23], v[22:23], v[36:37] op_sel_hi:[1,0]
	v_pk_mul_f32 v[20:21], v[20:21], v[36:37] op_sel_hi:[1,0]
	v_pk_mul_f32 v[24:25], v[18:19], v[36:37] op_sel_hi:[1,0]
	v_pk_mul_f32 v[18:19], v[16:17], v[36:37] op_sel_hi:[1,0]
	v_cvt_pk_bf16_f32 v16, v20, v21
	v_cvt_pk_bf16_f32 v17, v22, v23
	v_cvt_pk_bf16_f32 v18, v18, v19
	v_cvt_pk_bf16_f32 v19, v24, v25
	s_and_b64 vcc, exec, s[4:5]
	global_store_dwordx4 v[34:35], v[16:19], off offset:256
	s_cbranch_vccnz .LBB0_989
	s_nop 0
	v_cvt_f32_u32_e32 v16, v239
	v_fmamk_f32 v16, v16, 0x33000000, v213
	v_rsq_f32_e32 v32, v16
